# baseline (speedup 1.0000x reference)
; __global__ void __launch_bounds__(NTHREADS) fwd_megakernel(Params p_unused) {
;     ...
;   for (int li = 0; li < 2; ++li) {
;     const int l = 1 - li;
;     if (l == 0) {
;       CParamsPtr k = fresh_params();
;       convert_x(k->x, (bf16_t*)(k->ws + WS_XB), (size_t)MTOK * DM);
;     }
;     {
;       CParamsPtr k = fresh_params();
;       transpose_convert_wide(k->w_out + (size_t)l * DM * DM, (bf16_t*)(k->ws + WS_WOUTT) + (size_t)l * DM * DM, DM, DM, DM);
;     }
;     {
;       CParamsPtr k = fresh_params();
;       const int split = (l == 1 && (GEMM1_TILES % (int)gridDim.x) != 0) ? WIN_SPLIT_TILES : 0;
;       transpose_convert_wide(k->w_in + (size_t)l * DM * NIN, (bf16_t*)(k->ws + WS_WINT) + (size_t)l * NPAD * DM, DM, NIN,
;                              NPAD, split);
;     }
.LBB0_20:
	s_or_b64 exec, exec, s[6:7]
	s_mov_b32 s13, 0
	s_mov_b32 s3, s13
	s_mov_b32 s19, s13
	s_lshl_b64 s[14:15], s[2:3], 12
	s_lshl_b64 s[16:17], s[18:19], 12
	s_cmpk_lt_i32 s2, 0x400
	s_cselect_b64 s[6:7], -1, 0
	s_cmpk_lt_i32 s2, 0x80
	s_cselect_b64 s[24:25], -1, 0
	s_cmp_lt_i32 s2, 4
	s_cselect_b64 s[26:27], -1, 0
	s_abs_i32 s8, s18
	v_cvt_f32_u32_e32 v1, s8
	s_sub_i32 s9, 0, s8
	v_mov_b32_e32 v35, 0
	s_waitcnt lgkmcnt(0)
	v_rcp_iflag_f32_e32 v1, v1
	s_barrier
	ds_read_b96 v[2:4], v35
	v_mul_f32_e32 v1, 0x4f7ffffe, v1
	v_cvt_u32_f32_e32 v1, v1
	s_mov_b64 s[38:39], -1
	s_mov_b64 s[36:37], 0x2000000
	s_waitcnt lgkmcnt(0)
	v_readfirstlane_b32 s84, v2
	v_readfirstlane_b32 s12, v1
	s_mul_i32 s9, s9, s12
	s_mul_hi_u32 s9, s12, s9
	s_add_i32 s12, s12, s9
	s_mul_hi_u32 s9, s12, 0x7a0
	s_mul_i32 s9, s9, s8
	s_sub_i32 s9, 0x7a0, s9
	s_sub_i32 s12, s9, s8
	s_cmp_ge_u32 s9, s8
	s_cselect_b32 s9, s12, s9
	s_sub_i32 s12, s9, s8
	s_cmp_ge_u32 s9, s8
	s_cselect_b32 s8, s12, s9
	s_cmp_eq_u32 s8, 0
	s_cselect_b32 s56, 0, 0x900
	s_lshl_b64 s[28:29], s[2:3], 14
	s_or_b32 s28, s28, 16
	s_lshl_b64 s[30:31], s[18:19], 14
	s_lshl_b64 s[8:9], s[2:3], 13
	s_add_u32 s57, s8, 0x13400000
	v_cndmask_b32_e64 v1, 0, 1, s[6:7]
	v_readfirstlane_b32 s70, v3
	v_readfirstlane_b32 s33, v4
	s_addc_u32 s58, s9, 0
	s_lshl_b64 s[34:35], s[18:19], 13
	s_lshl_b32 s19, s2, 8
	s_lshl_b32 s3, s2, 6
	s_mov_b32 s12, 1
	s_mov_b64 s[8:9], 0
	s_mov_b64 s[40:41], 0x1ffffff
	v_cmp_ne_u32_e64 s[6:7], 1, v1
	s_movk_i32 s59, 0x404
	s_mov_b64 s[42:43], 0xf400000
	s_movk_i32 s60, 0x1000
	s_movk_i32 s61, 0x3c30
	s_mov_b32 s62, 0xf0c0
	s_movk_i32 s63, 0x104
	s_lshl_b32 s64, s18, 8
	s_branch .LBB0_22

;     ...
;     __syncthreads();
; #pragma unroll
;     for (int i = 0; i < 8; ++i) {
;       const int id = tid + i * 512;
;       const int r = id >> 6, c4 = (id & 63) * 4;
;       tile[r * 257 + c4 + 0] = v[i][0];
;       tile[r * 257 + c4 + 1] = v[i][1];
;       tile[r * 257 + c4 + 2] = v[i][2];
;       tile[r * 257 + c4 + 3] = v[i][3];
;     }
;     __syncthreads();
; #pragma unroll
;     for (int i = 0; i < 4; ++i) {
;       const int id = tid + i * 512;
;       const int n = id >> 3, kc = id & 7;
;       uint4 o;
;       o.x = pack2(tile[(kc * 8 + 0) * 257 + n], tile[(kc * 8 + 1) * 257 + n]);
;       o.y = pack2(tile[(kc * 8 + 2) * 257 + n], tile[(kc * 8 + 3) * 257 + n]);
;       o.z = pack2(tile[(kc * 8 + 4) * 257 + n], tile[(kc * 8 + 5) * 257 + n]);
;       o.w = pack2(tile[(kc * 8 + 6) * 257 + n], tile[(kc * 8 + 7) * 257 + n]);
;       *(uint4*)(dst + (size_t)(n0 + n) * K + k0 + kc * 8) = o;
;     }
; template <int l>
; __device__ __forceinline__ void layer_body(const XcdBarrier& xb) {
;     ...
;     if (l == 0) {
;       const int busy = GEMM1_TILES % (int)gridDim.x;
;       if (busy != 0 && (int)blockIdx.x >= busy) {
;         CParamsPtr k = fresh_params();
;         transpose_convert_wide(k->w_in + (size_t)DM * NIN, (bf16_t*)(k->ws + WS_WINT) + (size_t)NPAD * DM, DM, NIN, NPAD, 0,
;                                WIN_SPLIT_TILES, (int)blockIdx.x - busy, (int)gridDim.x - busy);
;       }
.LBB0_139:
	s_load_dword s8, s[10:11], 0x10
	s_load_dword s24, s[10:11], 0x0
	s_waitcnt lgkmcnt(0)
	s_lshr_b32 s8, s8, 16
	s_cmp_lg_u32 s8, 0
	s_cselect_b64 s[8:9], -1, 0
	s_cmp_lg_u64 s[8:9], 0
	s_addc_u32 s68, s24, 0
	v_cndmask_b32_e64 v0, 0, 1, s[8:9]
	s_abs_i32 s8, s68
	v_cvt_f32_u32_e32 v1, s8
	s_sub_i32 s9, 0, s8
	v_readfirstlane_b32 s25, v0
	v_rcp_iflag_f32_e32 v1, v1
	s_nop 0
	v_mul_f32_e32 v1, 0x4f7ffffe, v1
	v_cvt_u32_f32_e32 v1, v1
	s_nop 0
	v_readfirstlane_b32 s10, v1
	s_mul_i32 s9, s9, s10
	s_mul_hi_u32 s9, s10, s9
	s_add_i32 s10, s10, s9
	s_mul_hi_u32 s9, s10, 0x7a0
	s_mul_i32 s9, s9, s8
	s_sub_i32 s9, 0x7a0, s9
	s_sub_i32 s10, s9, s8
	s_cmp_ge_u32 s9, s8
	s_cselect_b32 s9, s10, s9
	s_sub_i32 s10, s9, s8
	s_cmp_ge_u32 s9, s8
	s_cselect_b32 s10, s10, s9
	s_cmp_eq_u32 s10, 0
	s_cselect_b64 s[8:9], -1, 0
	s_cmp_lt_i32 s2, s10
	s_cselect_b64 s[12:13], -1, 0
	s_or_b64 s[8:9], s[8:9], s[12:13]
	s_and_b64 vcc, exec, s[8:9]
	s_cbranch_vccnz .LBB0_159
	s_sub_i32 s14, s2, s10
	s_mov_b64 s[8:9], s[0:1]
	v_mov_b32_e32 v0, v254
	s_cmpk_gt_i32 s14, 0x8ff
	s_cbranch_scc1 .LBB0_159
	s_load_dwordx2 s[12:13], s[8:9], 0x8
	s_load_dwordx2 s[16:17], s[8:9], 0x68
	v_lshlrev_b32_e32 v1, 2, v0
	v_and_b32_e32 v38, 0xfc, v1
	v_lshlrev_b32_e32 v2, 2, v38
	v_mov_b32_e32 v3, 0
	s_waitcnt lgkmcnt(0)
	v_lshl_add_u64 v[4:5], s[12:13], 0, v[2:3]
	v_add_u32_e32 v1, 16, v2
	v_lshlrev_b32_e32 v2, 3, v0
	s_sub_i32 s15, s68, s10
	s_mov_b64 s[8:9], 0xf0c0000
	v_and_b32_e32 v2, 56, v2
	s_movk_i32 s10, 0x404
	v_lshl_add_u64 v[32:33], v[4:5], 0, s[8:9]
	v_mad_u32_u24 v4, v2, s10, 16
	v_lshlrev_b32_e32 v2, 1, v2
	v_add_u32_e32 v6, 0x800, v0
	v_lshl_add_u64 v[2:3], s[16:17], 0, v[2:3]
	s_mov_b64 s[8:9], 0x7a00000
	v_ashrrev_i32_e32 v45, 6, v6
	v_add_u32_e32 v6, 0xa00, v0
	v_lshl_add_u64 v[34:35], v[2:3], 0, s[8:9]
	v_ashrrev_i32_e32 v39, 3, v0
	v_ashrrev_i32_e32 v41, 6, v0
	v_add_u32_e32 v2, 0x200, v0
	v_add_u32_e32 v3, 0x400, v0
	v_add_u32_e32 v5, 0x600, v0
	v_ashrrev_i32_e32 v46, 6, v6
	v_add_u32_e32 v6, 0xc00, v0
	v_add_u32_e32 v0, 0xe00, v0
	v_ashrrev_i32_e32 v42, 6, v2
	v_ashrrev_i32_e32 v43, 6, v3
	v_ashrrev_i32_e32 v44, 6, v5
	v_ashrrev_i32_e32 v47, 6, v6
	v_ashrrev_i32_e32 v48, 6, v0
	v_mul_lo_u32 v0, v41, s10
	v_mul_lo_u32 v6, v42, s10
	v_mul_lo_u32 v7, v43, s10
	v_mul_lo_u32 v8, v44, s10
	v_mul_lo_u32 v9, v45, s10
	v_mul_lo_u32 v10, v46, s10
	v_mul_lo_u32 v11, v47, s10
	v_ashrrev_i32_e32 v49, 3, v2
	v_ashrrev_i32_e32 v51, 3, v3
	v_ashrrev_i32_e32 v53, 3, v5
	v_mul_lo_u32 v2, v48, s10
	v_lshl_add_u32 v40, v39, 2, v4
	v_lshl_add_u32 v50, v49, 2, v4
	v_lshl_add_u32 v52, v51, 2, v4
	v_lshl_add_u32 v54, v53, 2, v4
	s_lshl_b32 s16, s14, 8
	s_lshl_b32 s17, s15, 8
	s_movk_i32 s19, 0x3c30
	s_mov_b32 s26, 0xf0c0
	v_add_u32_e32 v55, v1, v0
	v_add_u32_e32 v56, v1, v6
	v_add_u32_e32 v57, v1, v7
	v_add_u32_e32 v58, v1, v8
	v_add_u32_e32 v59, v1, v9
	v_add_u32_e32 v60, v1, v10
	v_add_u32_e32 v61, v1, v11
	v_add_u32_e32 v62, v1, v2
	s_branch .LBB0_143
.LBB0_142:
	s_or_b64 exec, exec, s[12:13]
	s_barrier
	s_waitcnt vmcnt(7)
	ds_write2_b32 v55, v0, v1 offset1:1
	ds_write2_b32 v55, v2, v3 offset0:2 offset1:3
	s_waitcnt vmcnt(6)
	ds_write2_b32 v56, v8, v9 offset1:1
	ds_write2_b32 v56, v10, v11 offset0:2 offset1:3
	s_waitcnt vmcnt(5)
	ds_write2_b32 v57, v4, v5 offset1:1
	ds_write2_b32 v57, v6, v7 offset0:2 offset1:3
	s_waitcnt vmcnt(4)
	ds_write2_b32 v58, v16, v17 offset1:1
	ds_write2_b32 v58, v18, v19 offset0:2 offset1:3
	s_waitcnt vmcnt(3)
	ds_write2_b32 v59, v12, v13 offset1:1
	ds_write2_b32 v59, v14, v15 offset0:2 offset1:3
	s_waitcnt vmcnt(2)
	ds_write2_b32 v60, v24, v25 offset1:1
	ds_write2_b32 v60, v26, v27 offset0:2 offset1:3
	s_waitcnt vmcnt(1)
	ds_write2_b32 v61, v20, v21 offset1:1
	ds_write2_b32 v61, v22, v23 offset0:2 offset1:3
	s_waitcnt vmcnt(0)
	ds_write2_b32 v62, v28, v29 offset1:1
	ds_write2_b32 v62, v30, v31 offset0:2 offset1:3
	s_waitcnt lgkmcnt(0)
	s_barrier
	ds_read_b32 v0, v40
	ds_read_b32 v1, v40 offset:1028
	ds_read_b32 v2, v40 offset:2056
	ds_read_b32 v3, v40 offset:3084
	ds_read_b32 v6, v40 offset:4112
	ds_read_b32 v7, v40 offset:5140
	ds_read_b32 v8, v40 offset:6168
	ds_read_b32 v9, v40 offset:7196
	s_waitcnt lgkmcnt(6)
	v_cvt_pk_bf16_f32 v0, v0, v1
	s_waitcnt lgkmcnt(4)
	v_cvt_pk_bf16_f32 v1, v2, v3
	s_waitcnt lgkmcnt(2)
	v_cvt_pk_bf16_f32 v2, v6, v7
	v_add_u32_e32 v6, s8, v39
	s_waitcnt lgkmcnt(0)
	v_cvt_pk_bf16_f32 v3, v8, v9
	ds_read_b32 v8, v50
	ds_read_b32 v9, v50 offset:1028
	ds_read_b32 v10, v50 offset:2056
	ds_read_b32 v11, v50 offset:3084
	ds_read_b32 v12, v50 offset:4112
	ds_read_b32 v13, v50 offset:5140
	ds_read_b32 v14, v50 offset:6168
	ds_read_b32 v15, v50 offset:7196
	s_ashr_i32 s11, s10, 31
	v_ashrrev_i32_e32 v7, 31, v6
	v_lshl_add_u64 v[4:5], s[10:11], 1, v[34:35]
	v_lshlrev_b64 v[6:7], 13, v[6:7]
	v_lshl_add_u64 v[6:7], v[4:5], 0, v[6:7]
	global_store_dwordx4 v[6:7], v[0:3], off
	v_add_u32_e32 v6, s8, v49
	v_ashrrev_i32_e32 v7, 31, v6
	s_waitcnt lgkmcnt(6)
	v_cvt_pk_bf16_f32 v0, v8, v9
	s_waitcnt lgkmcnt(4)
	v_cvt_pk_bf16_f32 v1, v10, v11
	s_waitcnt lgkmcnt(2)
	v_cvt_pk_bf16_f32 v2, v12, v13
	s_waitcnt lgkmcnt(0)
	v_cvt_pk_bf16_f32 v3, v14, v15
	ds_read_b32 v8, v52
	ds_read_b32 v9, v52 offset:1028
	ds_read_b32 v10, v52 offset:2056
	ds_read_b32 v11, v52 offset:3084
	ds_read_b32 v12, v52 offset:4112
	ds_read_b32 v13, v52 offset:5140
	ds_read_b32 v14, v52 offset:6168
	ds_read_b32 v15, v52 offset:7196
	v_lshlrev_b64 v[6:7], 13, v[6:7]
	v_lshl_add_u64 v[6:7], v[4:5], 0, v[6:7]
	global_store_dwordx4 v[6:7], v[0:3], off
	v_add_u32_e32 v6, s8, v51
	v_ashrrev_i32_e32 v7, 31, v6
	s_waitcnt lgkmcnt(6)
	v_cvt_pk_bf16_f32 v0, v8, v9
	s_waitcnt lgkmcnt(4)
	v_cvt_pk_bf16_f32 v1, v10, v11
	s_waitcnt lgkmcnt(2)
	v_cvt_pk_bf16_f32 v2, v12, v13
	s_waitcnt lgkmcnt(0)
	v_cvt_pk_bf16_f32 v3, v14, v15
	v_lshlrev_b64 v[6:7], 13, v[6:7]
	ds_read_b32 v8, v54
	ds_read_b32 v9, v54 offset:1028
	ds_read_b32 v10, v54 offset:2056
	ds_read_b32 v11, v54 offset:3084
	ds_read_b32 v12, v54 offset:4112
	ds_read_b32 v13, v54 offset:5140
	ds_read_b32 v14, v54 offset:6168
	ds_read_b32 v15, v54 offset:7196
	v_lshl_add_u64 v[6:7], v[4:5], 0, v[6:7]
	global_store_dwordx4 v[6:7], v[0:3], off
	v_add_u32_e32 v6, s8, v53
	v_ashrrev_i32_e32 v7, 31, v6
	v_lshlrev_b64 v[6:7], 13, v[6:7]
	s_add_i32 s14, s14, s15
	s_add_i32 s16, s16, s17
	s_waitcnt lgkmcnt(6)
	v_cvt_pk_bf16_f32 v0, v8, v9
	s_waitcnt lgkmcnt(4)
	v_cvt_pk_bf16_f32 v1, v10, v11
	s_waitcnt lgkmcnt(2)
	v_cvt_pk_bf16_f32 v2, v12, v13
	s_waitcnt lgkmcnt(0)
	v_cvt_pk_bf16_f32 v3, v14, v15
	v_lshl_add_u64 v[4:5], v[4:5], 0, v[6:7]
	s_cmpk_lt_i32 s14, 0x900
	global_store_dwordx4 v[4:5], v[0:3], off
	s_cbranch_scc0 .LBB0_159
